# MIX phase entry: lambda dot products from two batches of dwordx4 loads instead of 32 serialized load steps; stacked
# baseline (speedup 1.0000x reference)
; #define LAS __attribute__((address_space(3)))
; __device__ __forceinline__ const float* arg_in(int k) { const int o = launder_s(k * 8); return *(const float* const*)((const char*)__builtin_amdgcn_kernarg_segment_ptr() + o); }
; #define ws (arg_ws())
; __global__ void __launch_bounds__(NTHR, 2) mk_fwd(Args a) {
;     ...
;             const float lambda_init = l == 0 ? 0.2f : 0.35550906759096926f;
;             float d1 = 0.f, d2 = 0.f;
;             for (int i = 0; i < 32; ++i) { d1 += arg_in(6)[l * 32 + i] * arg_in(7)[l * 32 + i]; d2 += arg_in(8)[l * 32 + i] * arg_in(9)[l * 32 + i]; }
;             const float lam = __expf(d1) - __expf(d2) + lambda_init;
;             const unsigned* kn2 = (const unsigned*)(ws + WS_KN2) + l * 8192;
;             {
;                 const bool useq = G == 256; const int xg = bx & 7;
;                 unsigned* qcnt = (unsigned*)(ws + WS_CTL) + 15000 + (l * 8 + xg) * 64;
;                 volatile LAS unsigned* qw = (volatile LAS unsigned*)(ldsl + MISC_OFF) + 16;
;                 if (useq) { if (tid == 0) qw[0] = __hip_atomic_fetch_add(qcnt, 1u, __ATOMIC_RELAXED, __HIP_MEMORY_SCOPE_AGENT); __syncthreads(); }
.LBB0_286:
	s_load_dwordx2 s[14:15], s[0:1], 0x30
	s_load_dwordx2 s[16:17], s[0:1], 0x38
	s_load_dwordx2 s[18:19], s[0:1], 0x40
	s_load_dwordx2 s[20:21], s[0:1], 0x48
	s_waitcnt lgkmcnt(0)
	s_add_u32 s14, s14, s38
	s_addc_u32 s15, s15, s39
	s_add_u32 s16, s16, s38
	s_addc_u32 s17, s17, s39
	s_add_u32 s18, s18, s38
	s_addc_u32 s19, s19, s39
	s_add_u32 s20, s20, s38
	s_addc_u32 s21, s21, s39
	global_load_dwordx4 v[2:5], v129, s[14:15]
	global_load_dwordx4 v[6:9], v129, s[14:15] offset:16
	global_load_dwordx4 v[10:13], v129, s[14:15] offset:32
	global_load_dwordx4 v[14:17], v129, s[14:15] offset:48
	global_load_dwordx4 v[18:21], v129, s[16:17]
	global_load_dwordx4 v[22:25], v129, s[16:17] offset:16
	global_load_dwordx4 v[26:29], v129, s[16:17] offset:32
	global_load_dwordx4 v[30:33], v129, s[16:17] offset:48
	global_load_dwordx4 v[34:37], v129, s[18:19]
	global_load_dwordx4 v[38:41], v129, s[18:19] offset:16
	global_load_dwordx4 v[42:45], v129, s[18:19] offset:32
	global_load_dwordx4 v[46:49], v129, s[18:19] offset:48
	global_load_dwordx4 v[50:53], v129, s[20:21]
	global_load_dwordx4 v[54:57], v129, s[20:21] offset:16
	global_load_dwordx4 v[58:61], v129, s[20:21] offset:32
	global_load_dwordx4 v[62:65], v129, s[20:21] offset:48
	s_waitcnt vmcnt(0)
	v_fma_f32 v0, v2, v18, v0
	v_fma_f32 v1, v34, v50, v1
	v_fma_f32 v0, v3, v19, v0
	v_fma_f32 v1, v35, v51, v1
	v_fma_f32 v0, v4, v20, v0
	v_fma_f32 v1, v36, v52, v1
	v_fma_f32 v0, v5, v21, v0
	v_fma_f32 v1, v37, v53, v1
	v_fma_f32 v0, v6, v22, v0
	v_fma_f32 v1, v38, v54, v1
	v_fma_f32 v0, v7, v23, v0
	v_fma_f32 v1, v39, v55, v1
	v_fma_f32 v0, v8, v24, v0
	v_fma_f32 v1, v40, v56, v1
	v_fma_f32 v0, v9, v25, v0
	v_fma_f32 v1, v41, v57, v1
	v_fma_f32 v0, v10, v26, v0
	v_fma_f32 v1, v42, v58, v1
	v_fma_f32 v0, v11, v27, v0
	v_fma_f32 v1, v43, v59, v1
	v_fma_f32 v0, v12, v28, v0
	v_fma_f32 v1, v44, v60, v1
	v_fma_f32 v0, v13, v29, v0
	v_fma_f32 v1, v45, v61, v1
	v_fma_f32 v0, v14, v30, v0
	v_fma_f32 v1, v46, v62, v1
	v_fma_f32 v0, v15, v31, v0
	v_fma_f32 v1, v47, v63, v1
	v_fma_f32 v0, v16, v32, v0
	v_fma_f32 v1, v48, v64, v1
	v_fma_f32 v0, v17, v33, v0
	v_fma_f32 v1, v49, v65, v1
	global_load_dwordx4 v[2:5], v129, s[14:15] offset:64
	global_load_dwordx4 v[6:9], v129, s[14:15] offset:80
	global_load_dwordx4 v[10:13], v129, s[14:15] offset:96
	global_load_dwordx4 v[14:17], v129, s[14:15] offset:112
	global_load_dwordx4 v[18:21], v129, s[16:17] offset:64
	global_load_dwordx4 v[22:25], v129, s[16:17] offset:80
	global_load_dwordx4 v[26:29], v129, s[16:17] offset:96
	global_load_dwordx4 v[30:33], v129, s[16:17] offset:112
	global_load_dwordx4 v[34:37], v129, s[18:19] offset:64
	global_load_dwordx4 v[38:41], v129, s[18:19] offset:80
	global_load_dwordx4 v[42:45], v129, s[18:19] offset:96
	global_load_dwordx4 v[46:49], v129, s[18:19] offset:112
	global_load_dwordx4 v[50:53], v129, s[20:21] offset:64
	global_load_dwordx4 v[54:57], v129, s[20:21] offset:80
	global_load_dwordx4 v[58:61], v129, s[20:21] offset:96
	global_load_dwordx4 v[62:65], v129, s[20:21] offset:112
	s_waitcnt vmcnt(0)
	v_fma_f32 v0, v2, v18, v0
	v_fma_f32 v1, v34, v50, v1
	v_fma_f32 v0, v3, v19, v0
	v_fma_f32 v1, v35, v51, v1
	v_fma_f32 v0, v4, v20, v0
	v_fma_f32 v1, v36, v52, v1
	v_fma_f32 v0, v5, v21, v0
	v_fma_f32 v1, v37, v53, v1
	v_fma_f32 v0, v6, v22, v0
	v_fma_f32 v1, v38, v54, v1
	v_fma_f32 v0, v7, v23, v0
	v_fma_f32 v1, v39, v55, v1
	v_fma_f32 v0, v8, v24, v0
	v_fma_f32 v1, v40, v56, v1
	v_fma_f32 v0, v9, v25, v0
	v_fma_f32 v1, v41, v57, v1
	v_fma_f32 v0, v10, v26, v0
	v_fma_f32 v1, v42, v58, v1
	v_fma_f32 v0, v11, v27, v0
	v_fma_f32 v1, v43, v59, v1
	v_fma_f32 v0, v12, v28, v0
	v_fma_f32 v1, v44, v60, v1
	v_fma_f32 v0, v13, v29, v0
	v_fma_f32 v1, v45, v61, v1
	v_fma_f32 v0, v14, v30, v0
	v_fma_f32 v1, v46, v62, v1
	v_fma_f32 v0, v15, v31, v0
	v_fma_f32 v1, v47, v63, v1
	v_fma_f32 v0, v16, v32, v0
	v_fma_f32 v1, v48, v64, v1
	v_fma_f32 v0, v17, v33, v0
	v_fma_f32 v1, v49, v65, v1
	s_movk_i32 s2, 0xa0
	s_ashr_i32 s15, s2, 31
	s_add_u32 s14, s0, s2
	s_addc_u32 s15, s1, s15
	s_movk_i32 s2, 0xa0
	s_load_dwordx2 s[40:41], s[14:15], 0x0
	s_ashr_i32 s15, s2, 31
	s_add_u32 s14, s0, s2
	s_addc_u32 s15, s1, s15
	s_load_dwordx2 s[14:15], s[14:15], 0x0
	s_lshl_b32 s38, s34, 9
	v_readlane_b32 s2, v253, 61
	s_or_b32 s70, s38, s2
	s_lshl_b64 s[16:17], s[70:71], 2
	s_waitcnt lgkmcnt(0)
	s_add_u32 s2, s14, s16
	s_addc_u32 s14, s15, s17
	v_writelane_b32 v255, s30, 22
	s_add_u32 s16, s2, 0xea60
	s_addc_u32 s17, s14, 0
	v_writelane_b32 v255, s31, 23
	v_readlane_b32 s14, v253, 56
	v_writelane_b32 v255, s16, 24
	v_readlane_b32 s15, v253, 57
	s_mov_b32 s84, 0x358637bd
	v_writelane_b32 v255, s17, 25
	s_and_b64 vcc, exec, s[14:15]
	s_cbranch_vccz .LBB0_293
	s_mov_b64 s[36:37], exec
	v_readlane_b32 s14, v253, 0
	v_readlane_b32 s15, v253, 1
	s_and_b64 s[14:15], s[36:37], s[14:15]
	s_mov_b64 exec, s[14:15]
	s_cbranch_execz .LBB0_292
	s_mov_b64 s[46:47], exec
	v_mbcnt_lo_u32_b32 v2, s46, 0
	v_mbcnt_hi_u32_b32 v2, s47, v2
	v_cmp_eq_u32_e32 vcc, 0, v2
	s_and_saveexec_b64 s[44:45], vcc
	s_cbranch_execz .LBB0_291
	s_bcnt1_i32_b64 s2, s[46:47]
	v_readlane_b32 s14, v255, 24
	v_mov_b32_e32 v3, s2
	v_readlane_b32 s15, v255, 25
	s_nop 4
	global_atomic_add v3, v129, v3, s[14:15] sc0
